# fp8 gate epilogue rewritten: rss loads hoisted, rstd batched, shift-term loads prefetched 3 row-groups ahead
# speedup vs baseline: 1.0235x; 1.0104x over previous
.LBB0_577:
	v_lshl_add_u32 v0, s51, 8, v181
	v_ashrrev_i32_e32 v1, 31, v0
	v_lshlrev_b64 v[2:3], 6, v[0:1]
	s_nop 15
	s_nop 15
	v_lshl_add_u64 v[2:3], v[166:167], 0, v[2:3]
	s_mov_b32 s26, 0x2000
	s_mov_b32 s27, 0
	s_mov_b32 s52, 0x48000
	s_mov_b32 s53, 0
	s_mov_b32 s54, 0x168000
	s_mov_b32 s55, 0
	s_mov_b32 s11, 0x9000
	global_load_dwordx4 v[198:201], v[2:3], off
	global_load_dwordx4 v[202:205], v[2:3], off offset:1024
	global_load_dwordx4 v[206:209], v[2:3], off offset:2048
	global_load_dwordx4 v[210:213], v[2:3], off offset:3072
	v_lshl_add_u64 v[240:241], v[2:3], 0, s[26:27]
	global_load_dwordx4 v[224:227], v[240:241], off
	global_load_dwordx4 v[228:231], v[240:241], off offset:1024
	global_load_dwordx4 v[232:235], v[240:241], off offset:2048
	global_load_dwordx4 v[236:239], v[240:241], off offset:3072
	v_lshl_add_u32 v20, s50, 8, v183
	v_ashrrev_i32_e32 v21, 31, v20
	v_lshlrev_b64 v[4:5], 2, v[20:21]
	v_lshlrev_b64 v[8:9], 1, v[20:21]
	v_mov_b64_e32 v[2:3], s[8:9]
	v_mov_b64_e32 v[6:7], s[6:7]
	v_mad_i64_i32 v[6:7], s[24:25], v0, s68, v[6:7]
	v_lshl_add_u64 v[6:7], v[6:7], 0, v[8:9]
	v_xor_b32_e32 v1, 16, v221
	v_lshlrev_b32_e32 v1, 2, v1
	v_xor_b32_e32 v10, 32, v221
	v_lshlrev_b32_e32 v10, 2, v10
	v_cmp_gt_i32_e32 vcc, s33, v0
	v_add_u32_e32 v11, s40, v0
	v_add_u32_e32 v187, s41, v0
	v_cndmask_b32_e32 v11, v11, v187, vcc
	v_cmp_gt_i32_e32 vcc, s90, v11
	v_add_u32_e32 v187, 0xffffc000, v11
	v_lshrrev_b32_e32 v187, 3, v187
	v_ashrrev_i32_e32 v194, 11, v11
	v_add_u32_e32 v187, 8, v187
	v_cndmask_b32_e32 v11, v187, v194, vcc
	v_mad_i64_i32 v[240:241], s[24:25], v11, s11, v[2:3]
	v_lshl_add_u64 v[240:241], v[240:241], 0, v[4:5]
	global_load_dwordx4 v[172:175], v[240:241], off
	global_load_dwordx4 v[176:179], v[240:241], off offset:16
	global_load_dwordx4 v[188:191], v[240:241], off offset:512
	global_load_dwordx4 v[12:15], v[240:241], off offset:528
	s_waitcnt vmcnt(4)
	v_add_f32_e32 v16, v198, v199
	v_add_f32_e32 v17, v200, v201
	v_add_f32_e32 v18, v202, v203
	v_add_f32_e32 v19, v204, v205
	v_add_f32_e32 v20, v206, v207
	v_add_f32_e32 v21, v208, v209
	v_add_f32_e32 v22, v210, v211
	v_add_f32_e32 v23, v212, v213
	v_add_f32_e32 v24, v224, v225
	v_add_f32_e32 v25, v226, v227
	v_add_f32_e32 v26, v228, v229
	v_add_f32_e32 v27, v230, v231
	v_add_f32_e32 v28, v232, v233
	v_add_f32_e32 v29, v234, v235
	v_add_f32_e32 v30, v236, v237
	v_add_f32_e32 v31, v238, v239
	v_add_f32_e32 v16, v16, v17
	v_add_f32_e32 v18, v18, v19
	v_add_f32_e32 v20, v20, v21
	v_add_f32_e32 v22, v22, v23
	v_add_f32_e32 v24, v24, v25
	v_add_f32_e32 v26, v26, v27
	v_add_f32_e32 v28, v28, v29
	v_add_f32_e32 v30, v30, v31
	ds_bpermute_b32 v17, v1, v16
	ds_bpermute_b32 v19, v1, v18
	ds_bpermute_b32 v21, v1, v20
	ds_bpermute_b32 v23, v1, v22
	ds_bpermute_b32 v25, v1, v24
	ds_bpermute_b32 v27, v1, v26
	ds_bpermute_b32 v29, v1, v28
	ds_bpermute_b32 v31, v1, v30
	v_or_b32_e32 v197, 16, v0
	v_cmp_gt_i32_e32 vcc, s33, v197
	v_add_u32_e32 v11, s42, v0
	v_add_u32_e32 v187, s41, v197
	v_cndmask_b32_e32 v11, v11, v187, vcc
	v_cmp_gt_i32_e32 vcc, s90, v11
	v_add_u32_e32 v187, 0xffffc000, v11
	v_lshrrev_b32_e32 v187, 3, v187
	v_ashrrev_i32_e32 v194, 11, v11
	v_add_u32_e32 v187, 8, v187
	v_cndmask_b32_e32 v11, v187, v194, vcc
	v_mad_i64_i32 v[240:241], s[24:25], v11, s11, v[2:3]
	v_lshl_add_u64 v[240:241], v[240:241], 0, v[4:5]
	global_load_dwordx4 v[198:201], v[240:241], off
	global_load_dwordx4 v[202:205], v[240:241], off offset:16
	global_load_dwordx4 v[206:209], v[240:241], off offset:512
	global_load_dwordx4 v[210:213], v[240:241], off offset:528
	s_waitcnt lgkmcnt(0)
	v_add_f32_e32 v16, v16, v17
	v_add_f32_e32 v18, v18, v19
	v_add_f32_e32 v20, v20, v21
	v_add_f32_e32 v22, v22, v23
	v_add_f32_e32 v24, v24, v25
	v_add_f32_e32 v26, v26, v27
	v_add_f32_e32 v28, v28, v29
	v_add_f32_e32 v30, v30, v31
	ds_bpermute_b32 v17, v10, v16
	ds_bpermute_b32 v19, v10, v18
	ds_bpermute_b32 v21, v10, v20
	ds_bpermute_b32 v23, v10, v22
	ds_bpermute_b32 v25, v10, v24
	ds_bpermute_b32 v27, v10, v26
	ds_bpermute_b32 v29, v10, v28
	ds_bpermute_b32 v31, v10, v30
	v_or_b32_e32 v197, 32, v0
	v_cmp_gt_i32_e32 vcc, s33, v197
	v_add_u32_e32 v11, s43, v0
	v_add_u32_e32 v187, s41, v197
	v_cndmask_b32_e32 v11, v11, v187, vcc
	v_cmp_gt_i32_e32 vcc, s90, v11
	v_add_u32_e32 v187, 0xffffc000, v11
	v_lshrrev_b32_e32 v187, 3, v187
	v_ashrrev_i32_e32 v194, 11, v11
	v_add_u32_e32 v187, 8, v187
	v_cndmask_b32_e32 v11, v187, v194, vcc
	v_mad_i64_i32 v[240:241], s[24:25], v11, s11, v[2:3]
	v_lshl_add_u64 v[240:241], v[240:241], 0, v[4:5]
	global_load_dwordx4 v[224:227], v[240:241], off
	global_load_dwordx4 v[228:231], v[240:241], off offset:16
	global_load_dwordx4 v[232:235], v[240:241], off offset:512
	global_load_dwordx4 v[236:239], v[240:241], off offset:528
	s_waitcnt lgkmcnt(0)
	v_add_f32_e32 v16, v16, v17
	v_add_f32_e32 v18, v18, v19
	v_add_f32_e32 v20, v20, v21
	v_add_f32_e32 v22, v22, v23
	v_add_f32_e32 v24, v24, v25
	v_add_f32_e32 v26, v26, v27
	v_add_f32_e32 v28, v28, v29
	v_add_f32_e32 v30, v30, v31
	v_fmamk_f32 v16, v16, 0x3a800000, v216
	v_fmamk_f32 v18, v18, 0x3a800000, v216
	v_fmamk_f32 v20, v20, 0x3a800000, v216
	v_fmamk_f32 v22, v22, 0x3a800000, v216
	v_fmamk_f32 v24, v24, 0x3a800000, v216
	v_fmamk_f32 v26, v26, 0x3a800000, v216
	v_fmamk_f32 v28, v28, 0x3a800000, v216
	v_fmamk_f32 v30, v30, 0x3a800000, v216
	v_rsq_f32_e32 v16, v16
	v_rsq_f32_e32 v18, v18
	v_rsq_f32_e32 v20, v20
	v_rsq_f32_e32 v22, v22
	v_rsq_f32_e32 v24, v24
	v_rsq_f32_e32 v26, v26
	v_rsq_f32_e32 v28, v28
	v_rsq_f32_e32 v30, v30
	s_nop 0
	s_waitcnt vmcnt(8)
	v_pk_fma_f32 v[174:175], v[158:159], v[16:17], v[174:175] op_sel_hi:[1,0,1]
	v_pk_fma_f32 v[172:173], v[156:157], v[16:17], v[172:173] op_sel_hi:[1,0,1]
	v_pk_fma_f32 v[178:179], v[154:155], v[16:17], v[178:179] op_sel_hi:[1,0,1]
	v_pk_fma_f32 v[176:177], v[152:153], v[16:17], v[176:177] op_sel_hi:[1,0,1]
	v_mul_f32_e32 v172, 0xbfb8aa3b, v172
	v_mul_f32_e32 v173, 0xbfb8aa3b, v173
	v_mul_f32_e32 v174, 0xbfb8aa3b, v174
	v_mul_f32_e32 v175, 0xbfb8aa3b, v175
	v_mul_f32_e32 v176, 0xbfb8aa3b, v176
	v_mul_f32_e32 v177, 0xbfb8aa3b, v177
	v_mul_f32_e32 v178, 0xbfb8aa3b, v178
	v_mul_f32_e32 v179, 0xbfb8aa3b, v179
	v_exp_f32_e32 v172, v172
	v_exp_f32_e32 v173, v173
	v_exp_f32_e32 v174, v174
	v_exp_f32_e32 v175, v175
	v_exp_f32_e32 v176, v176
	v_exp_f32_e32 v177, v177
	v_exp_f32_e32 v178, v178
	v_exp_f32_e32 v179, v179
	v_add_f32_e32 v172, 1.0, v172
	v_add_f32_e32 v173, 1.0, v173
	v_add_f32_e32 v174, 1.0, v174
	v_add_f32_e32 v175, 1.0, v175
	v_add_f32_e32 v176, 1.0, v176
	v_add_f32_e32 v177, 1.0, v177
	v_add_f32_e32 v178, 1.0, v178
	v_add_f32_e32 v179, 1.0, v179
	v_rcp_f32_e32 v172, v172
	v_rcp_f32_e32 v173, v173
	v_rcp_f32_e32 v174, v174
	v_rcp_f32_e32 v175, v175
	v_rcp_f32_e32 v176, v176
	v_rcp_f32_e32 v177, v177
	v_rcp_f32_e32 v178, v178
	v_rcp_f32_e32 v179, v179
	v_cvt_pk_bf16_f32 v172, v172, v173
	v_cvt_pk_bf16_f32 v173, v174, v175
	v_cvt_pk_bf16_f32 v174, v176, v177
	v_cvt_pk_bf16_f32 v175, v178, v179
	global_store_dwordx4 v[6:7], v[172:175], off
	v_lshl_add_u64 v[192:193], v[6:7], 0, s[52:53]
	v_pk_fma_f32 v[190:191], v[150:151], v[16:17], v[190:191] op_sel_hi:[1,0,1]
	v_pk_fma_f32 v[188:189], v[148:149], v[16:17], v[188:189] op_sel_hi:[1,0,1]
	v_pk_fma_f32 v[14:15], v[146:147], v[16:17], v[14:15] op_sel_hi:[1,0,1]
	v_pk_fma_f32 v[12:13], v[144:145], v[16:17], v[12:13] op_sel_hi:[1,0,1]
	v_mul_f32_e32 v188, 0xbfb8aa3b, v188
	v_mul_f32_e32 v189, 0xbfb8aa3b, v189
	v_mul_f32_e32 v190, 0xbfb8aa3b, v190
	v_mul_f32_e32 v191, 0xbfb8aa3b, v191
	v_mul_f32_e32 v12, 0xbfb8aa3b, v12
	v_mul_f32_e32 v13, 0xbfb8aa3b, v13
	v_mul_f32_e32 v14, 0xbfb8aa3b, v14
	v_mul_f32_e32 v15, 0xbfb8aa3b, v15
	v_exp_f32_e32 v188, v188
	v_exp_f32_e32 v189, v189
	v_exp_f32_e32 v190, v190
	v_exp_f32_e32 v191, v191
	v_exp_f32_e32 v12, v12
	v_exp_f32_e32 v13, v13
	v_exp_f32_e32 v14, v14
	v_exp_f32_e32 v15, v15
	v_add_f32_e32 v188, 1.0, v188
	v_add_f32_e32 v189, 1.0, v189
	v_add_f32_e32 v190, 1.0, v190
	v_add_f32_e32 v191, 1.0, v191
	v_add_f32_e32 v12, 1.0, v12
	v_add_f32_e32 v13, 1.0, v13
	v_add_f32_e32 v14, 1.0, v14
	v_add_f32_e32 v15, 1.0, v15
	v_rcp_f32_e32 v188, v188
	v_rcp_f32_e32 v189, v189
	v_rcp_f32_e32 v190, v190
	v_rcp_f32_e32 v191, v191
	v_rcp_f32_e32 v12, v12
	v_rcp_f32_e32 v13, v13
	v_rcp_f32_e32 v14, v14
	v_rcp_f32_e32 v15, v15
	v_cvt_pk_bf16_f32 v188, v188, v189
	v_cvt_pk_bf16_f32 v189, v190, v191
	v_cvt_pk_bf16_f32 v190, v12, v13
	v_cvt_pk_bf16_f32 v191, v14, v15
	global_store_dwordx4 v[6:7], v[188:191], off offset:256
	v_or_b32_e32 v197, 48, v0
	v_cmp_gt_i32_e32 vcc, s33, v197
	v_add_u32_e32 v11, s44, v0
	v_add_u32_e32 v187, s41, v197
	v_cndmask_b32_e32 v11, v11, v187, vcc
	v_cmp_gt_i32_e32 vcc, s90, v11
	v_add_u32_e32 v187, 0xffffc000, v11
	v_lshrrev_b32_e32 v187, 3, v187
	v_ashrrev_i32_e32 v194, 11, v11
	v_add_u32_e32 v187, 8, v187
	v_cndmask_b32_e32 v11, v187, v194, vcc
	v_mad_i64_i32 v[240:241], s[24:25], v11, s11, v[2:3]
	v_lshl_add_u64 v[240:241], v[240:241], 0, v[4:5]
	global_load_dwordx4 v[172:175], v[240:241], off
	global_load_dwordx4 v[176:179], v[240:241], off offset:16
	global_load_dwordx4 v[188:191], v[240:241], off offset:512
	global_load_dwordx4 v[12:15], v[240:241], off offset:528
	s_waitcnt vmcnt(10)
	v_pk_fma_f32 v[200:201], v[142:143], v[18:19], v[200:201] op_sel_hi:[1,0,1]
	v_pk_fma_f32 v[198:199], v[140:141], v[18:19], v[198:199] op_sel_hi:[1,0,1]
	v_pk_fma_f32 v[204:205], v[138:139], v[18:19], v[204:205] op_sel_hi:[1,0,1]
	v_pk_fma_f32 v[202:203], v[136:137], v[18:19], v[202:203] op_sel_hi:[1,0,1]
	v_mul_f32_e32 v198, 0xbfb8aa3b, v198
	v_mul_f32_e32 v199, 0xbfb8aa3b, v199
	v_mul_f32_e32 v200, 0xbfb8aa3b, v200
	v_mul_f32_e32 v201, 0xbfb8aa3b, v201
	v_mul_f32_e32 v202, 0xbfb8aa3b, v202
	v_mul_f32_e32 v203, 0xbfb8aa3b, v203
	v_mul_f32_e32 v204, 0xbfb8aa3b, v204
	v_mul_f32_e32 v205, 0xbfb8aa3b, v205
	v_exp_f32_e32 v198, v198
	v_exp_f32_e32 v199, v199
	v_exp_f32_e32 v200, v200
	v_exp_f32_e32 v201, v201
	v_exp_f32_e32 v202, v202
	v_exp_f32_e32 v203, v203
	v_exp_f32_e32 v204, v204
	v_exp_f32_e32 v205, v205
	v_add_f32_e32 v198, 1.0, v198
	v_add_f32_e32 v199, 1.0, v199
	v_add_f32_e32 v200, 1.0, v200
	v_add_f32_e32 v201, 1.0, v201
	v_add_f32_e32 v202, 1.0, v202
	v_add_f32_e32 v203, 1.0, v203
	v_add_f32_e32 v204, 1.0, v204
	v_add_f32_e32 v205, 1.0, v205
	v_rcp_f32_e32 v198, v198
	v_rcp_f32_e32 v199, v199
	v_rcp_f32_e32 v200, v200
	v_rcp_f32_e32 v201, v201
	v_rcp_f32_e32 v202, v202
	v_rcp_f32_e32 v203, v203
	v_rcp_f32_e32 v204, v204
	v_rcp_f32_e32 v205, v205
	v_cvt_pk_bf16_f32 v198, v198, v199
	v_cvt_pk_bf16_f32 v199, v200, v201
	v_cvt_pk_bf16_f32 v200, v202, v203
	v_cvt_pk_bf16_f32 v201, v204, v205
	global_store_dwordx4 v[192:193], v[198:201], off
	v_lshl_add_u64 v[6:7], v[192:193], 0, s[52:53]
	v_pk_fma_f32 v[208:209], v[134:135], v[18:19], v[208:209] op_sel_hi:[1,0,1]
	v_pk_fma_f32 v[206:207], v[132:133], v[18:19], v[206:207] op_sel_hi:[1,0,1]
	v_pk_fma_f32 v[212:213], v[130:131], v[18:19], v[212:213] op_sel_hi:[1,0,1]
	v_pk_fma_f32 v[210:211], v[128:129], v[18:19], v[210:211] op_sel_hi:[1,0,1]
	v_mul_f32_e32 v206, 0xbfb8aa3b, v206
	v_mul_f32_e32 v207, 0xbfb8aa3b, v207
	v_mul_f32_e32 v208, 0xbfb8aa3b, v208
	v_mul_f32_e32 v209, 0xbfb8aa3b, v209
	v_mul_f32_e32 v210, 0xbfb8aa3b, v210
	v_mul_f32_e32 v211, 0xbfb8aa3b, v211
	v_mul_f32_e32 v212, 0xbfb8aa3b, v212
	v_mul_f32_e32 v213, 0xbfb8aa3b, v213
	v_exp_f32_e32 v206, v206
	v_exp_f32_e32 v207, v207
	v_exp_f32_e32 v208, v208
	v_exp_f32_e32 v209, v209
	v_exp_f32_e32 v210, v210
	v_exp_f32_e32 v211, v211
	v_exp_f32_e32 v212, v212
	v_exp_f32_e32 v213, v213
	v_add_f32_e32 v206, 1.0, v206
	v_add_f32_e32 v207, 1.0, v207
	v_add_f32_e32 v208, 1.0, v208
	v_add_f32_e32 v209, 1.0, v209
	v_add_f32_e32 v210, 1.0, v210
	v_add_f32_e32 v211, 1.0, v211
	v_add_f32_e32 v212, 1.0, v212
	v_add_f32_e32 v213, 1.0, v213
	v_rcp_f32_e32 v206, v206
	v_rcp_f32_e32 v207, v207
	v_rcp_f32_e32 v208, v208
	v_rcp_f32_e32 v209, v209
	v_rcp_f32_e32 v210, v210
	v_rcp_f32_e32 v211, v211
	v_rcp_f32_e32 v212, v212
	v_rcp_f32_e32 v213, v213
	v_cvt_pk_bf16_f32 v206, v206, v207
	v_cvt_pk_bf16_f32 v207, v208, v209
	v_cvt_pk_bf16_f32 v208, v210, v211
	v_cvt_pk_bf16_f32 v209, v212, v213
	global_store_dwordx4 v[192:193], v[206:209], off offset:256
	v_add_u32_e32 v197, 0x80, v0
	v_cmp_gt_i32_e32 vcc, s33, v197
	v_add_u32_e32 v11, s45, v0
	v_add_u32_e32 v187, s41, v197
	v_cndmask_b32_e32 v11, v11, v187, vcc
	v_cmp_gt_i32_e32 vcc, s90, v11
	v_add_u32_e32 v187, 0xffffc000, v11
	v_lshrrev_b32_e32 v187, 3, v187
	v_ashrrev_i32_e32 v194, 11, v11
	v_add_u32_e32 v187, 8, v187
	v_cndmask_b32_e32 v11, v187, v194, vcc
	v_mad_i64_i32 v[240:241], s[24:25], v11, s11, v[2:3]
	v_lshl_add_u64 v[240:241], v[240:241], 0, v[4:5]
	global_load_dwordx4 v[198:201], v[240:241], off
	global_load_dwordx4 v[202:205], v[240:241], off offset:16
	global_load_dwordx4 v[206:209], v[240:241], off offset:512
	global_load_dwordx4 v[210:213], v[240:241], off offset:528
	s_waitcnt vmcnt(12)
	v_pk_fma_f32 v[226:227], v[126:127], v[20:21], v[226:227] op_sel_hi:[1,0,1]
	v_pk_fma_f32 v[224:225], v[124:125], v[20:21], v[224:225] op_sel_hi:[1,0,1]
	v_pk_fma_f32 v[230:231], v[122:123], v[20:21], v[230:231] op_sel_hi:[1,0,1]
	v_pk_fma_f32 v[228:229], v[120:121], v[20:21], v[228:229] op_sel_hi:[1,0,1]
	v_mul_f32_e32 v224, 0xbfb8aa3b, v224
	v_mul_f32_e32 v225, 0xbfb8aa3b, v225
	v_mul_f32_e32 v226, 0xbfb8aa3b, v226
	v_mul_f32_e32 v227, 0xbfb8aa3b, v227
	v_mul_f32_e32 v228, 0xbfb8aa3b, v228
	v_mul_f32_e32 v229, 0xbfb8aa3b, v229
	v_mul_f32_e32 v230, 0xbfb8aa3b, v230
	v_mul_f32_e32 v231, 0xbfb8aa3b, v231
	v_exp_f32_e32 v224, v224
	v_exp_f32_e32 v225, v225
	v_exp_f32_e32 v226, v226
	v_exp_f32_e32 v227, v227
	v_exp_f32_e32 v228, v228
	v_exp_f32_e32 v229, v229
	v_exp_f32_e32 v230, v230
	v_exp_f32_e32 v231, v231
	v_add_f32_e32 v224, 1.0, v224
	v_add_f32_e32 v225, 1.0, v225
	v_add_f32_e32 v226, 1.0, v226
	v_add_f32_e32 v227, 1.0, v227
	v_add_f32_e32 v228, 1.0, v228
	v_add_f32_e32 v229, 1.0, v229
	v_add_f32_e32 v230, 1.0, v230
	v_add_f32_e32 v231, 1.0, v231
	v_rcp_f32_e32 v224, v224
	v_rcp_f32_e32 v225, v225
	v_rcp_f32_e32 v226, v226
	v_rcp_f32_e32 v227, v227
	v_rcp_f32_e32 v228, v228
	v_rcp_f32_e32 v229, v229
	v_rcp_f32_e32 v230, v230
	v_rcp_f32_e32 v231, v231
	v_cvt_pk_bf16_f32 v224, v224, v225
	v_cvt_pk_bf16_f32 v225, v226, v227
	v_cvt_pk_bf16_f32 v226, v228, v229
	v_cvt_pk_bf16_f32 v227, v230, v231
	global_store_dwordx4 v[6:7], v[224:227], off
	v_lshl_add_u64 v[192:193], v[6:7], 0, s[52:53]
	v_pk_fma_f32 v[234:235], v[118:119], v[20:21], v[234:235] op_sel_hi:[1,0,1]
	v_pk_fma_f32 v[232:233], v[116:117], v[20:21], v[232:233] op_sel_hi:[1,0,1]
	v_pk_fma_f32 v[238:239], v[114:115], v[20:21], v[238:239] op_sel_hi:[1,0,1]
	v_pk_fma_f32 v[236:237], v[112:113], v[20:21], v[236:237] op_sel_hi:[1,0,1]
	v_mul_f32_e32 v232, 0xbfb8aa3b, v232
	v_mul_f32_e32 v233, 0xbfb8aa3b, v233
	v_mul_f32_e32 v234, 0xbfb8aa3b, v234
	v_mul_f32_e32 v235, 0xbfb8aa3b, v235
	v_mul_f32_e32 v236, 0xbfb8aa3b, v236
	v_mul_f32_e32 v237, 0xbfb8aa3b, v237
	v_mul_f32_e32 v238, 0xbfb8aa3b, v238
	v_mul_f32_e32 v239, 0xbfb8aa3b, v239
	v_exp_f32_e32 v232, v232
	v_exp_f32_e32 v233, v233
	v_exp_f32_e32 v234, v234
	v_exp_f32_e32 v235, v235
	v_exp_f32_e32 v236, v236
	v_exp_f32_e32 v237, v237
	v_exp_f32_e32 v238, v238
	v_exp_f32_e32 v239, v239
	v_add_f32_e32 v232, 1.0, v232
	v_add_f32_e32 v233, 1.0, v233
	v_add_f32_e32 v234, 1.0, v234
	v_add_f32_e32 v235, 1.0, v235
	v_add_f32_e32 v236, 1.0, v236
	v_add_f32_e32 v237, 1.0, v237
	v_add_f32_e32 v238, 1.0, v238
	v_add_f32_e32 v239, 1.0, v239
	v_rcp_f32_e32 v232, v232
	v_rcp_f32_e32 v233, v233
	v_rcp_f32_e32 v234, v234
	v_rcp_f32_e32 v235, v235
	v_rcp_f32_e32 v236, v236
	v_rcp_f32_e32 v237, v237
	v_rcp_f32_e32 v238, v238
	v_rcp_f32_e32 v239, v239
	v_cvt_pk_bf16_f32 v232, v232, v233
	v_cvt_pk_bf16_f32 v233, v234, v235
	v_cvt_pk_bf16_f32 v234, v236, v237
	v_cvt_pk_bf16_f32 v235, v238, v239
	global_store_dwordx4 v[6:7], v[232:235], off offset:256
	v_add_u32_e32 v197, 0x90, v0
	v_cmp_gt_i32_e32 vcc, s33, v197
	v_add_u32_e32 v11, s46, v0
	v_add_u32_e32 v187, s41, v197
	v_cndmask_b32_e32 v11, v11, v187, vcc
	v_cmp_gt_i32_e32 vcc, s90, v11
	v_add_u32_e32 v187, 0xffffc000, v11
	v_lshrrev_b32_e32 v187, 3, v187
	v_ashrrev_i32_e32 v194, 11, v11
	v_add_u32_e32 v187, 8, v187
	v_cndmask_b32_e32 v11, v187, v194, vcc
	v_mad_i64_i32 v[240:241], s[24:25], v11, s11, v[2:3]
	v_lshl_add_u64 v[240:241], v[240:241], 0, v[4:5]
	global_load_dwordx4 v[224:227], v[240:241], off
	global_load_dwordx4 v[228:231], v[240:241], off offset:16
	global_load_dwordx4 v[232:235], v[240:241], off offset:512
	global_load_dwordx4 v[236:239], v[240:241], off offset:528
	s_waitcnt vmcnt(12)
	v_pk_fma_f32 v[174:175], v[110:111], v[22:23], v[174:175] op_sel_hi:[1,0,1]
	v_pk_fma_f32 v[172:173], v[108:109], v[22:23], v[172:173] op_sel_hi:[1,0,1]
	v_pk_fma_f32 v[178:179], v[106:107], v[22:23], v[178:179] op_sel_hi:[1,0,1]
	v_pk_fma_f32 v[176:177], v[104:105], v[22:23], v[176:177] op_sel_hi:[1,0,1]
	v_mul_f32_e32 v172, 0xbfb8aa3b, v172
	v_mul_f32_e32 v173, 0xbfb8aa3b, v173
	v_mul_f32_e32 v174, 0xbfb8aa3b, v174
	v_mul_f32_e32 v175, 0xbfb8aa3b, v175
	v_mul_f32_e32 v176, 0xbfb8aa3b, v176
	v_mul_f32_e32 v177, 0xbfb8aa3b, v177
	v_mul_f32_e32 v178, 0xbfb8aa3b, v178
	v_mul_f32_e32 v179, 0xbfb8aa3b, v179
	v_exp_f32_e32 v172, v172
	v_exp_f32_e32 v173, v173
	v_exp_f32_e32 v174, v174
	v_exp_f32_e32 v175, v175
	v_exp_f32_e32 v176, v176
	v_exp_f32_e32 v177, v177
	v_exp_f32_e32 v178, v178
	v_exp_f32_e32 v179, v179
	v_add_f32_e32 v172, 1.0, v172
	v_add_f32_e32 v173, 1.0, v173
	v_add_f32_e32 v174, 1.0, v174
	v_add_f32_e32 v175, 1.0, v175
	v_add_f32_e32 v176, 1.0, v176
	v_add_f32_e32 v177, 1.0, v177
	v_add_f32_e32 v178, 1.0, v178
	v_add_f32_e32 v179, 1.0, v179
	v_rcp_f32_e32 v172, v172
	v_rcp_f32_e32 v173, v173
	v_rcp_f32_e32 v174, v174
	v_rcp_f32_e32 v175, v175
	v_rcp_f32_e32 v176, v176
	v_rcp_f32_e32 v177, v177
	v_rcp_f32_e32 v178, v178
	v_rcp_f32_e32 v179, v179
	v_cvt_pk_bf16_f32 v172, v172, v173
	v_cvt_pk_bf16_f32 v173, v174, v175
	v_cvt_pk_bf16_f32 v174, v176, v177
	v_cvt_pk_bf16_f32 v175, v178, v179
	global_store_dwordx4 v[192:193], v[172:175], off
	v_lshl_add_u64 v[6:7], v[192:193], 0, s[54:55]
	v_pk_fma_f32 v[190:191], v[102:103], v[22:23], v[190:191] op_sel_hi:[1,0,1]
	v_pk_fma_f32 v[188:189], v[100:101], v[22:23], v[188:189] op_sel_hi:[1,0,1]
	v_pk_fma_f32 v[14:15], v[98:99], v[22:23], v[14:15] op_sel_hi:[1,0,1]
	v_pk_fma_f32 v[12:13], v[96:97], v[22:23], v[12:13] op_sel_hi:[1,0,1]
	v_mul_f32_e32 v188, 0xbfb8aa3b, v188
	v_mul_f32_e32 v189, 0xbfb8aa3b, v189
	v_mul_f32_e32 v190, 0xbfb8aa3b, v190
	v_mul_f32_e32 v191, 0xbfb8aa3b, v191
	v_mul_f32_e32 v12, 0xbfb8aa3b, v12
	v_mul_f32_e32 v13, 0xbfb8aa3b, v13
	v_mul_f32_e32 v14, 0xbfb8aa3b, v14
	v_mul_f32_e32 v15, 0xbfb8aa3b, v15
	v_exp_f32_e32 v188, v188
	v_exp_f32_e32 v189, v189
	v_exp_f32_e32 v190, v190
	v_exp_f32_e32 v191, v191
	v_exp_f32_e32 v12, v12
	v_exp_f32_e32 v13, v13
	v_exp_f32_e32 v14, v14
	v_exp_f32_e32 v15, v15
	v_add_f32_e32 v188, 1.0, v188
	v_add_f32_e32 v189, 1.0, v189
	v_add_f32_e32 v190, 1.0, v190
	v_add_f32_e32 v191, 1.0, v191
	v_add_f32_e32 v12, 1.0, v12
	v_add_f32_e32 v13, 1.0, v13
	v_add_f32_e32 v14, 1.0, v14
	v_add_f32_e32 v15, 1.0, v15
	v_rcp_f32_e32 v188, v188
	v_rcp_f32_e32 v189, v189
	v_rcp_f32_e32 v190, v190
	v_rcp_f32_e32 v191, v191
	v_rcp_f32_e32 v12, v12
	v_rcp_f32_e32 v13, v13
	v_rcp_f32_e32 v14, v14
	v_rcp_f32_e32 v15, v15
	v_cvt_pk_bf16_f32 v188, v188, v189
	v_cvt_pk_bf16_f32 v189, v190, v191
	v_cvt_pk_bf16_f32 v190, v12, v13
	v_cvt_pk_bf16_f32 v191, v14, v15
	global_store_dwordx4 v[192:193], v[188:191], off offset:256
	v_add_u32_e32 v197, 0xa0, v0
	v_cmp_gt_i32_e32 vcc, s33, v197
	v_add_u32_e32 v11, s47, v0
	v_add_u32_e32 v187, s41, v197
	v_cndmask_b32_e32 v11, v11, v187, vcc
	v_cmp_gt_i32_e32 vcc, s90, v11
	v_add_u32_e32 v187, 0xffffc000, v11
	v_lshrrev_b32_e32 v187, 3, v187
	v_ashrrev_i32_e32 v194, 11, v11
	v_add_u32_e32 v187, 8, v187
	v_cndmask_b32_e32 v11, v187, v194, vcc
	v_mad_i64_i32 v[240:241], s[24:25], v11, s11, v[2:3]
	v_lshl_add_u64 v[240:241], v[240:241], 0, v[4:5]
	global_load_dwordx4 v[172:175], v[240:241], off
	global_load_dwordx4 v[176:179], v[240:241], off offset:16
	global_load_dwordx4 v[188:191], v[240:241], off offset:512
	global_load_dwordx4 v[12:15], v[240:241], off offset:528
	s_waitcnt vmcnt(12)
	v_pk_fma_f32 v[200:201], v[94:95], v[24:25], v[200:201] op_sel_hi:[1,0,1]
	v_pk_fma_f32 v[198:199], v[92:93], v[24:25], v[198:199] op_sel_hi:[1,0,1]
	v_pk_fma_f32 v[204:205], v[90:91], v[24:25], v[204:205] op_sel_hi:[1,0,1]
	v_pk_fma_f32 v[202:203], v[88:89], v[24:25], v[202:203] op_sel_hi:[1,0,1]
	v_mul_f32_e32 v198, 0xbfb8aa3b, v198
	v_mul_f32_e32 v199, 0xbfb8aa3b, v199
	v_mul_f32_e32 v200, 0xbfb8aa3b, v200
	v_mul_f32_e32 v201, 0xbfb8aa3b, v201
	v_mul_f32_e32 v202, 0xbfb8aa3b, v202
	v_mul_f32_e32 v203, 0xbfb8aa3b, v203
	v_mul_f32_e32 v204, 0xbfb8aa3b, v204
	v_mul_f32_e32 v205, 0xbfb8aa3b, v205
	v_exp_f32_e32 v198, v198
	v_exp_f32_e32 v199, v199
	v_exp_f32_e32 v200, v200
	v_exp_f32_e32 v201, v201
	v_exp_f32_e32 v202, v202
	v_exp_f32_e32 v203, v203
	v_exp_f32_e32 v204, v204
	v_exp_f32_e32 v205, v205
	v_add_f32_e32 v198, 1.0, v198
	v_add_f32_e32 v199, 1.0, v199
	v_add_f32_e32 v200, 1.0, v200
	v_add_f32_e32 v201, 1.0, v201
	v_add_f32_e32 v202, 1.0, v202
	v_add_f32_e32 v203, 1.0, v203
	v_add_f32_e32 v204, 1.0, v204
	v_add_f32_e32 v205, 1.0, v205
	v_rcp_f32_e32 v198, v198
	v_rcp_f32_e32 v199, v199
	v_rcp_f32_e32 v200, v200
	v_rcp_f32_e32 v201, v201
	v_rcp_f32_e32 v202, v202
	v_rcp_f32_e32 v203, v203
	v_rcp_f32_e32 v204, v204
	v_rcp_f32_e32 v205, v205
	v_cvt_pk_bf16_f32 v198, v198, v199
	v_cvt_pk_bf16_f32 v199, v200, v201
	v_cvt_pk_bf16_f32 v200, v202, v203
	v_cvt_pk_bf16_f32 v201, v204, v205
	global_store_dwordx4 v[6:7], v[198:201], off
	v_lshl_add_u64 v[192:193], v[6:7], 0, s[52:53]
	v_pk_fma_f32 v[208:209], v[86:87], v[24:25], v[208:209] op_sel_hi:[1,0,1]
	v_pk_fma_f32 v[206:207], v[84:85], v[24:25], v[206:207] op_sel_hi:[1,0,1]
	v_pk_fma_f32 v[212:213], v[82:83], v[24:25], v[212:213] op_sel_hi:[1,0,1]
	v_pk_fma_f32 v[210:211], v[80:81], v[24:25], v[210:211] op_sel_hi:[1,0,1]
	v_mul_f32_e32 v206, 0xbfb8aa3b, v206
	v_mul_f32_e32 v207, 0xbfb8aa3b, v207
	v_mul_f32_e32 v208, 0xbfb8aa3b, v208
	v_mul_f32_e32 v209, 0xbfb8aa3b, v209
	v_mul_f32_e32 v210, 0xbfb8aa3b, v210
	v_mul_f32_e32 v211, 0xbfb8aa3b, v211
	v_mul_f32_e32 v212, 0xbfb8aa3b, v212
	v_mul_f32_e32 v213, 0xbfb8aa3b, v213
	v_exp_f32_e32 v206, v206
	v_exp_f32_e32 v207, v207
	v_exp_f32_e32 v208, v208
	v_exp_f32_e32 v209, v209
	v_exp_f32_e32 v210, v210
	v_exp_f32_e32 v211, v211
	v_exp_f32_e32 v212, v212
	v_exp_f32_e32 v213, v213
	v_add_f32_e32 v206, 1.0, v206
	v_add_f32_e32 v207, 1.0, v207
	v_add_f32_e32 v208, 1.0, v208
	v_add_f32_e32 v209, 1.0, v209
	v_add_f32_e32 v210, 1.0, v210
	v_add_f32_e32 v211, 1.0, v211
	v_add_f32_e32 v212, 1.0, v212
	v_add_f32_e32 v213, 1.0, v213
	v_rcp_f32_e32 v206, v206
	v_rcp_f32_e32 v207, v207
	v_rcp_f32_e32 v208, v208
	v_rcp_f32_e32 v209, v209
	v_rcp_f32_e32 v210, v210
	v_rcp_f32_e32 v211, v211
	v_rcp_f32_e32 v212, v212
	v_rcp_f32_e32 v213, v213
	v_cvt_pk_bf16_f32 v206, v206, v207
	v_cvt_pk_bf16_f32 v207, v208, v209
	v_cvt_pk_bf16_f32 v208, v210, v211
	v_cvt_pk_bf16_f32 v209, v212, v213
	global_store_dwordx4 v[6:7], v[206:209], off offset:256
	v_add_u32_e32 v197, 0xb0, v0
	v_cmp_gt_i32_e32 vcc, s33, v197
	v_add_u32_e32 v11, s48, v0
	v_add_u32_e32 v187, s41, v197
	v_cndmask_b32_e32 v11, v11, v187, vcc
	v_cmp_gt_i32_e32 vcc, s90, v11
	v_add_u32_e32 v187, 0xffffc000, v11
	v_lshrrev_b32_e32 v187, 3, v187
	v_ashrrev_i32_e32 v194, 11, v11
	v_add_u32_e32 v187, 8, v187
	v_cndmask_b32_e32 v11, v187, v194, vcc
	v_mad_i64_i32 v[240:241], s[24:25], v11, s11, v[2:3]
	v_lshl_add_u64 v[240:241], v[240:241], 0, v[4:5]
	global_load_dwordx4 v[198:201], v[240:241], off
	global_load_dwordx4 v[202:205], v[240:241], off offset:16
	global_load_dwordx4 v[206:209], v[240:241], off offset:512
	global_load_dwordx4 v[210:213], v[240:241], off offset:528
	s_waitcnt vmcnt(12)
	v_pk_fma_f32 v[226:227], v[78:79], v[26:27], v[226:227] op_sel_hi:[1,0,1]
	v_pk_fma_f32 v[224:225], v[76:77], v[26:27], v[224:225] op_sel_hi:[1,0,1]
	v_pk_fma_f32 v[230:231], v[74:75], v[26:27], v[230:231] op_sel_hi:[1,0,1]
	v_pk_fma_f32 v[228:229], v[72:73], v[26:27], v[228:229] op_sel_hi:[1,0,1]
	v_mul_f32_e32 v224, 0xbfb8aa3b, v224
	v_mul_f32_e32 v225, 0xbfb8aa3b, v225
	v_mul_f32_e32 v226, 0xbfb8aa3b, v226
	v_mul_f32_e32 v227, 0xbfb8aa3b, v227
	v_mul_f32_e32 v228, 0xbfb8aa3b, v228
	v_mul_f32_e32 v229, 0xbfb8aa3b, v229
	v_mul_f32_e32 v230, 0xbfb8aa3b, v230
	v_mul_f32_e32 v231, 0xbfb8aa3b, v231
	v_exp_f32_e32 v224, v224
	v_exp_f32_e32 v225, v225
	v_exp_f32_e32 v226, v226
	v_exp_f32_e32 v227, v227
	v_exp_f32_e32 v228, v228
	v_exp_f32_e32 v229, v229
	v_exp_f32_e32 v230, v230
	v_exp_f32_e32 v231, v231
	v_add_f32_e32 v224, 1.0, v224
	v_add_f32_e32 v225, 1.0, v225
	v_add_f32_e32 v226, 1.0, v226
	v_add_f32_e32 v227, 1.0, v227
	v_add_f32_e32 v228, 1.0, v228
	v_add_f32_e32 v229, 1.0, v229
	v_add_f32_e32 v230, 1.0, v230
	v_add_f32_e32 v231, 1.0, v231
	v_rcp_f32_e32 v224, v224
	v_rcp_f32_e32 v225, v225
	v_rcp_f32_e32 v226, v226
	v_rcp_f32_e32 v227, v227
	v_rcp_f32_e32 v228, v228
	v_rcp_f32_e32 v229, v229
	v_rcp_f32_e32 v230, v230
	v_rcp_f32_e32 v231, v231
	v_cvt_pk_bf16_f32 v224, v224, v225
	v_cvt_pk_bf16_f32 v225, v226, v227
	v_cvt_pk_bf16_f32 v226, v228, v229
	v_cvt_pk_bf16_f32 v227, v230, v231
	global_store_dwordx4 v[192:193], v[224:227], off
	v_lshl_add_u64 v[6:7], v[192:193], 0, s[52:53]
	v_pk_fma_f32 v[234:235], v[70:71], v[26:27], v[234:235] op_sel_hi:[1,0,1]
	v_pk_fma_f32 v[232:233], v[68:69], v[26:27], v[232:233] op_sel_hi:[1,0,1]
	v_pk_fma_f32 v[238:239], v[66:67], v[26:27], v[238:239] op_sel_hi:[1,0,1]
	v_pk_fma_f32 v[236:237], v[64:65], v[26:27], v[236:237] op_sel_hi:[1,0,1]
	v_mul_f32_e32 v232, 0xbfb8aa3b, v232
	v_mul_f32_e32 v233, 0xbfb8aa3b, v233
	v_mul_f32_e32 v234, 0xbfb8aa3b, v234
	v_mul_f32_e32 v235, 0xbfb8aa3b, v235
	v_mul_f32_e32 v236, 0xbfb8aa3b, v236
	v_mul_f32_e32 v237, 0xbfb8aa3b, v237
	v_mul_f32_e32 v238, 0xbfb8aa3b, v238
	v_mul_f32_e32 v239, 0xbfb8aa3b, v239
	v_exp_f32_e32 v232, v232
	v_exp_f32_e32 v233, v233
	v_exp_f32_e32 v234, v234
	v_exp_f32_e32 v235, v235
	v_exp_f32_e32 v236, v236
	v_exp_f32_e32 v237, v237
	v_exp_f32_e32 v238, v238
	v_exp_f32_e32 v239, v239
	v_add_f32_e32 v232, 1.0, v232
	v_add_f32_e32 v233, 1.0, v233
	v_add_f32_e32 v234, 1.0, v234
	v_add_f32_e32 v235, 1.0, v235
	v_add_f32_e32 v236, 1.0, v236
	v_add_f32_e32 v237, 1.0, v237
	v_add_f32_e32 v238, 1.0, v238
	v_add_f32_e32 v239, 1.0, v239
	v_rcp_f32_e32 v232, v232
	v_rcp_f32_e32 v233, v233
	v_rcp_f32_e32 v234, v234
	v_rcp_f32_e32 v235, v235
	v_rcp_f32_e32 v236, v236
	v_rcp_f32_e32 v237, v237
	v_rcp_f32_e32 v238, v238
	v_rcp_f32_e32 v239, v239
	v_cvt_pk_bf16_f32 v232, v232, v233
	v_cvt_pk_bf16_f32 v233, v234, v235
	v_cvt_pk_bf16_f32 v234, v236, v237
	v_cvt_pk_bf16_f32 v235, v238, v239
	global_store_dwordx4 v[192:193], v[232:235], off offset:256
	s_waitcnt vmcnt(8)
	v_pk_fma_f32 v[174:175], v[62:63], v[28:29], v[174:175] op_sel_hi:[1,0,1]
	v_pk_fma_f32 v[172:173], v[60:61], v[28:29], v[172:173] op_sel_hi:[1,0,1]
	v_pk_fma_f32 v[178:179], v[58:59], v[28:29], v[178:179] op_sel_hi:[1,0,1]
	v_pk_fma_f32 v[176:177], v[56:57], v[28:29], v[176:177] op_sel_hi:[1,0,1]
	v_mul_f32_e32 v172, 0xbfb8aa3b, v172
	v_mul_f32_e32 v173, 0xbfb8aa3b, v173
	v_mul_f32_e32 v174, 0xbfb8aa3b, v174
	v_mul_f32_e32 v175, 0xbfb8aa3b, v175
	v_mul_f32_e32 v176, 0xbfb8aa3b, v176
	v_mul_f32_e32 v177, 0xbfb8aa3b, v177
	v_mul_f32_e32 v178, 0xbfb8aa3b, v178
	v_mul_f32_e32 v179, 0xbfb8aa3b, v179
	v_exp_f32_e32 v172, v172
	v_exp_f32_e32 v173, v173
	v_exp_f32_e32 v174, v174
	v_exp_f32_e32 v175, v175
	v_exp_f32_e32 v176, v176
	v_exp_f32_e32 v177, v177
	v_exp_f32_e32 v178, v178
	v_exp_f32_e32 v179, v179
	v_add_f32_e32 v172, 1.0, v172
	v_add_f32_e32 v173, 1.0, v173
	v_add_f32_e32 v174, 1.0, v174
	v_add_f32_e32 v175, 1.0, v175
	v_add_f32_e32 v176, 1.0, v176
	v_add_f32_e32 v177, 1.0, v177
	v_add_f32_e32 v178, 1.0, v178
	v_add_f32_e32 v179, 1.0, v179
	v_rcp_f32_e32 v172, v172
	v_rcp_f32_e32 v173, v173
	v_rcp_f32_e32 v174, v174
	v_rcp_f32_e32 v175, v175
	v_rcp_f32_e32 v176, v176
	v_rcp_f32_e32 v177, v177
	v_rcp_f32_e32 v178, v178
	v_rcp_f32_e32 v179, v179
	v_cvt_pk_bf16_f32 v172, v172, v173
	v_cvt_pk_bf16_f32 v173, v174, v175
	v_cvt_pk_bf16_f32 v174, v176, v177
	v_cvt_pk_bf16_f32 v175, v178, v179
	global_store_dwordx4 v[6:7], v[172:175], off
	v_lshl_add_u64 v[192:193], v[6:7], 0, s[52:53]
	v_pk_fma_f32 v[190:191], v[54:55], v[28:29], v[190:191] op_sel_hi:[1,0,1]
	v_pk_fma_f32 v[188:189], v[52:53], v[28:29], v[188:189] op_sel_hi:[1,0,1]
	v_pk_fma_f32 v[14:15], v[50:51], v[28:29], v[14:15] op_sel_hi:[1,0,1]
	v_pk_fma_f32 v[12:13], v[48:49], v[28:29], v[12:13] op_sel_hi:[1,0,1]
	v_mul_f32_e32 v188, 0xbfb8aa3b, v188
	v_mul_f32_e32 v189, 0xbfb8aa3b, v189
	v_mul_f32_e32 v190, 0xbfb8aa3b, v190
	v_mul_f32_e32 v191, 0xbfb8aa3b, v191
	v_mul_f32_e32 v12, 0xbfb8aa3b, v12
	v_mul_f32_e32 v13, 0xbfb8aa3b, v13
	v_mul_f32_e32 v14, 0xbfb8aa3b, v14
	v_mul_f32_e32 v15, 0xbfb8aa3b, v15
	v_exp_f32_e32 v188, v188
	v_exp_f32_e32 v189, v189
	v_exp_f32_e32 v190, v190
	v_exp_f32_e32 v191, v191
	v_exp_f32_e32 v12, v12
	v_exp_f32_e32 v13, v13
	v_exp_f32_e32 v14, v14
	v_exp_f32_e32 v15, v15
	v_add_f32_e32 v188, 1.0, v188
	v_add_f32_e32 v189, 1.0, v189
	v_add_f32_e32 v190, 1.0, v190
	v_add_f32_e32 v191, 1.0, v191
	v_add_f32_e32 v12, 1.0, v12
	v_add_f32_e32 v13, 1.0, v13
	v_add_f32_e32 v14, 1.0, v14
	v_add_f32_e32 v15, 1.0, v15
	v_rcp_f32_e32 v188, v188
	v_rcp_f32_e32 v189, v189
	v_rcp_f32_e32 v190, v190
	v_rcp_f32_e32 v191, v191
	v_rcp_f32_e32 v12, v12
	v_rcp_f32_e32 v13, v13
	v_rcp_f32_e32 v14, v14
	v_rcp_f32_e32 v15, v15
	v_cvt_pk_bf16_f32 v188, v188, v189
	v_cvt_pk_bf16_f32 v189, v190, v191
	v_cvt_pk_bf16_f32 v190, v12, v13
	v_cvt_pk_bf16_f32 v191, v14, v15
	global_store_dwordx4 v[6:7], v[188:191], off offset:256
	s_waitcnt vmcnt(4)
	v_pk_fma_f32 v[200:201], v[46:47], v[30:31], v[200:201] op_sel_hi:[1,0,1]
	v_pk_fma_f32 v[198:199], v[44:45], v[30:31], v[198:199] op_sel_hi:[1,0,1]
	v_pk_fma_f32 v[204:205], v[42:43], v[30:31], v[204:205] op_sel_hi:[1,0,1]
	v_pk_fma_f32 v[202:203], v[40:41], v[30:31], v[202:203] op_sel_hi:[1,0,1]
	v_mul_f32_e32 v198, 0xbfb8aa3b, v198
	v_mul_f32_e32 v199, 0xbfb8aa3b, v199
	v_mul_f32_e32 v200, 0xbfb8aa3b, v200
	v_mul_f32_e32 v201, 0xbfb8aa3b, v201
	v_mul_f32_e32 v202, 0xbfb8aa3b, v202
	v_mul_f32_e32 v203, 0xbfb8aa3b, v203
	v_mul_f32_e32 v204, 0xbfb8aa3b, v204
	v_mul_f32_e32 v205, 0xbfb8aa3b, v205
	v_exp_f32_e32 v198, v198
	v_exp_f32_e32 v199, v199
	v_exp_f32_e32 v200, v200
	v_exp_f32_e32 v201, v201
	v_exp_f32_e32 v202, v202
	v_exp_f32_e32 v203, v203
	v_exp_f32_e32 v204, v204
	v_exp_f32_e32 v205, v205
	v_add_f32_e32 v198, 1.0, v198
	v_add_f32_e32 v199, 1.0, v199
	v_add_f32_e32 v200, 1.0, v200
	v_add_f32_e32 v201, 1.0, v201
	v_add_f32_e32 v202, 1.0, v202
	v_add_f32_e32 v203, 1.0, v203
	v_add_f32_e32 v204, 1.0, v204
	v_add_f32_e32 v205, 1.0, v205
	v_rcp_f32_e32 v198, v198
	v_rcp_f32_e32 v199, v199
	v_rcp_f32_e32 v200, v200
	v_rcp_f32_e32 v201, v201
	v_rcp_f32_e32 v202, v202
	v_rcp_f32_e32 v203, v203
	v_rcp_f32_e32 v204, v204
	v_rcp_f32_e32 v205, v205
	v_cvt_pk_bf16_f32 v198, v198, v199
	v_cvt_pk_bf16_f32 v199, v200, v201
	v_cvt_pk_bf16_f32 v200, v202, v203
	v_cvt_pk_bf16_f32 v201, v204, v205
	global_store_dwordx4 v[192:193], v[198:201], off
	v_pk_fma_f32 v[208:209], v[38:39], v[30:31], v[208:209] op_sel_hi:[1,0,1]
	v_pk_fma_f32 v[206:207], v[36:37], v[30:31], v[206:207] op_sel_hi:[1,0,1]
	v_pk_fma_f32 v[212:213], v[34:35], v[30:31], v[212:213] op_sel_hi:[1,0,1]
	v_pk_fma_f32 v[210:211], v[32:33], v[30:31], v[210:211] op_sel_hi:[1,0,1]
	v_mul_f32_e32 v206, 0xbfb8aa3b, v206
	v_mul_f32_e32 v207, 0xbfb8aa3b, v207
	v_mul_f32_e32 v208, 0xbfb8aa3b, v208
	v_mul_f32_e32 v209, 0xbfb8aa3b, v209
	v_mul_f32_e32 v210, 0xbfb8aa3b, v210
	v_mul_f32_e32 v211, 0xbfb8aa3b, v211
	v_mul_f32_e32 v212, 0xbfb8aa3b, v212
	v_mul_f32_e32 v213, 0xbfb8aa3b, v213
	v_exp_f32_e32 v206, v206
	v_exp_f32_e32 v207, v207
	v_exp_f32_e32 v208, v208
	v_exp_f32_e32 v209, v209
	v_exp_f32_e32 v210, v210
	v_exp_f32_e32 v211, v211
	v_exp_f32_e32 v212, v212
	v_exp_f32_e32 v213, v213
	v_add_f32_e32 v206, 1.0, v206
	v_add_f32_e32 v207, 1.0, v207
	v_add_f32_e32 v208, 1.0, v208
	v_add_f32_e32 v209, 1.0, v209
	v_add_f32_e32 v210, 1.0, v210
	v_add_f32_e32 v211, 1.0, v211
	v_add_f32_e32 v212, 1.0, v212
	v_add_f32_e32 v213, 1.0, v213
	v_rcp_f32_e32 v206, v206
	v_rcp_f32_e32 v207, v207
	v_rcp_f32_e32 v208, v208
	v_rcp_f32_e32 v209, v209
	v_rcp_f32_e32 v210, v210
	v_rcp_f32_e32 v211, v211
	v_rcp_f32_e32 v212, v212
	v_rcp_f32_e32 v213, v213
	v_cvt_pk_bf16_f32 v206, v206, v207
	v_cvt_pk_bf16_f32 v207, v208, v209
	v_cvt_pk_bf16_f32 v208, v210, v211
	v_cvt_pk_bf16_f32 v209, v212, v213
	global_store_dwordx4 v[192:193], v[206:209], off offset:256
	s_andn2_b64 vcc, exec, s[20:21]
	s_mov_b64 s[20:21], -1
	s_cbranch_vccnz .LBB0_570
	s_andn2_b64 vcc, exec, s[12:13]
	s_cbranch_vccnz .LBB0_569
	s_barrier
	s_branch .LBB0_569
